# LDS-DMA placement: the two V^T pieces issue three MFMA gaps after the K pieces instead of in one burst after the barrier
# speedup vs baseline: 1.1125x; 1.0048x over previous
;   DI void gload_k(int t) {
;     const int row0 = rowk0 + t * 64;
;     const u16* kt = Kb + (size_t)row0 * kpitch;
;     const u16* pt = KPEb + (size_t)row0 * 32;
; #pragma unroll
;     for (int q = 0; q < NKL; ++q) {
;       const int c = tid + 256 * q, cc = c % KCH;
;       rk[q] = ldg16(((DQK == 96 && cc >= 8) ? pt : kt) + koff[q]);
;     }
;   template <int PAR>
;   DI void step(int t, f32x16 (&cur)[2], f32x16 (&nxt)[2]) {
;     if (t + 1 < nt) sstore_k(PAR ^ 1);
;     if (t > 0) sstore_v(PAR);
;     __syncthreads();
;     if (t + 1 < nt) qk(PAR ^ 1, nxt);
;     float mx = fmaxf(cur[0][0], cur[1][0]);
; #pragma unroll
;     for (int i = 1; i < 16; ++i) mx = fmaxf(fmaxf(cur[0][i], cur[1][i]), mx);
;     if (__builtin_amdgcn_ballot_w64(mx > ATT_THR) != 0ull) {
;       asm volatile("" ::: "memory");
;       mx = fmaxf(mx, xhalf(mx));
;       const float want = mref + fmaxf(mx, 0.f);
;       const float mn = __uint_as_float(pack2(want, 0.f) << 16);
;       const float d = mn - mref;
;       const float alpha = __builtin_amdgcn_exp2f(-d);
;       mref = mn;
;       l *= alpha;
; #pragma unroll
;       for (int a = 0; a < 2; ++a)
; #pragma unroll
;         for (int i = 0; i < 16; ++i) { o[a][i] *= alpha; cur[a][i] -= d; nxt[a][i] -= d; }
;       u32x4 q4 = {h == 0 ? (pack2(-mn, 0.f) & 0xffffu) : 0u, 0u, 0u, 0u};
;       qm = __builtin_bit_cast(bf16x8, q4);
;     }
;     float psum = 0.f;
; #pragma unroll
;     for (int kb2 = 0; kb2 < 2; ++kb2)
; #pragma unroll
;       for (int i = 0; i < 16; ++i) { const float pv = __builtin_amdgcn_exp2f(cur[kb2][i]); cur[kb2][i] = pv; psum += pv; }
;     l += psum;
;     if (t + 2 < nt) gload_k(t + 2);
;     if (t + 1 < nt) gload_v(t + 1);
;     const u16* vb = sV + PAR * VBUF + r * GP + h * 8;
; #pragma unroll
;     for (int kb2 = 0; kb2 < 2; ++kb2)
; #pragma unroll
;       for (int s2 = 0; s2 < 2; ++s2) {
;         u32x4 pk = {pack2(cur[kb2][8 * s2], cur[kb2][8 * s2 + 1]), pack2(cur[kb2][8 * s2 + 2], cur[kb2][8 * s2 + 3]),
;                     pack2(cur[kb2][8 * s2 + 4], cur[kb2][8 * s2 + 5]), pack2(cur[kb2][8 * s2 + 6], cur[kb2][8 * s2 + 7])};
;         const bf16x8 pf = __builtin_bit_cast(bf16x8, pk);
; #pragma unroll
;         for (int db = 0; db < 2; ++db) {
;           const bf16x8 a = *(const bf16x8*)(vb + db * 32 * GP + kb2 * 32 + s2 * 16);
;           o[db] = MFMA(a, pf, o[db]);
;         }
;       }
;   }
.Lgf_skipKA:
	ds_read_b128 v[96:99], v156 offset:18432
	ds_read_b128 v[100:103], v156 offset:22528
	ds_read_b128 v[104:107], v157 offset:18432
	ds_read_b128 v[108:111], v157 offset:22528
	v_mfma_f32_32x32x16_bf16 v[80:95], v[112:115], v[144:147], v[80:95]
	ds_read_b128 v[112:115], v158 offset:18432
	v_exp_f32_e32 v63, v63
	v_add_f32_e32 v183, v61, v183
	v_cvt_pk_bf16_f32 v56, v56, v57
	v_add_f32_e32 v182, v62, v182
	v_cvt_pk_bf16_f32 v57, v58, v59
	v_add_f32_e32 v183, v63, v183
	v_mfma_f32_32x32x16_bf16 v[64:79], v[116:119], v[144:147], v[64:79]
	ds_read_b128 v[116:119], v158 offset:22528
	v_cvt_pk_bf16_f32 v58, v60, v61
	v_cvt_pk_bf16_f32 v59, v62, v63
	v_exp_f32_e32 v32, v32
	v_exp_f32_e32 v33, v33
	v_exp_f32_e32 v34, v34
	v_add_f32_e32 v182, v32, v182
	v_mfma_f32_32x32x16_bf16 v[80:95], v[120:123], v[148:151], v[80:95]
	ds_read_b128 v[120:123], v159 offset:18432
	v_exp_f32_e32 v35, v35
	v_add_f32_e32 v183, v33, v183
	v_exp_f32_e32 v36, v36
	v_add_f32_e32 v182, v34, v182
	v_exp_f32_e32 v37, v37
	v_add_f32_e32 v183, v35, v183
	s_add_i32 m0, s46, 27648
	s_nop 0
	global_load_lds_dwordx4 v[160:161], off
	global_load_lds_dwordx4 v[162:163], off offset:1024
	v_lshl_add_u64 v[160:161], v[160:161], 0, s[84:85]
	v_lshl_add_u64 v[162:163], v[162:163], 0, s[84:85]
	v_mfma_f32_32x32x16_bf16 v[64:79], v[124:127], v[148:151], v[64:79]
	ds_read_b128 v[124:127], v159 offset:22528
	v_exp_f32_e32 v38, v38
	v_add_f32_e32 v182, v36, v182
	v_exp_f32_e32 v39, v39
	v_add_f32_e32 v183, v37, v183
	v_cvt_pk_bf16_f32 v32, v32, v33
	v_add_f32_e32 v182, v38, v182
	s_waitcnt lgkmcnt(4)
	v_mfma_f32_32x32x16_bf16 v[16:31], v[96:99], v[48:51], v[16:31]
	ds_read_b128 v[96:99], v152
	v_cvt_pk_bf16_f32 v33, v34, v35
	v_add_f32_e32 v183, v39, v183
	v_cvt_pk_bf16_f32 v34, v36, v37
	v_cvt_pk_bf16_f32 v35, v38, v39
	v_exp_f32_e32 v40, v40
	v_mfma_f32_32x32x16_bf16 v[0:15], v[100:103], v[48:51], v[0:15]
	ds_read_b128 v[100:103], v152 offset:4096
	v_exp_f32_e32 v41, v41
	v_exp_f32_e32 v42, v42
	v_add_f32_e32 v182, v40, v182
	v_exp_f32_e32 v43, v43
	v_add_f32_e32 v183, v41, v183
	v_mfma_f32_32x32x16_bf16 v[16:31], v[104:107], v[56:59], v[16:31]
	ds_read_b128 v[104:107], v153
	v_exp_f32_e32 v44, v44
	v_add_f32_e32 v182, v42, v182
	v_exp_f32_e32 v45, v45
	v_add_f32_e32 v183, v43, v183
	v_exp_f32_e32 v46, v46
	v_mfma_f32_32x32x16_bf16 v[0:15], v[108:111], v[56:59], v[0:15]
	ds_read_b128 v[108:111], v153 offset:4096
	v_add_f32_e32 v182, v44, v182
	v_exp_f32_e32 v47, v47
	v_add_f32_e32 v183, v45, v183
	v_cvt_pk_bf16_f32 v40, v40, v41
	v_add_f32_e32 v182, v46, v182
	s_waitcnt lgkmcnt(4)
	v_mfma_f32_32x32x16_bf16 v[16:31], v[112:115], v[32:35], v[16:31]
	ds_read_b128 v[112:115], v154
	v_cvt_pk_bf16_f32 v41, v42, v43
	v_add_f32_e32 v183, v47, v183
	v_cvt_pk_bf16_f32 v42, v44, v45
	v_cvt_pk_bf16_f32 v43, v46, v47
	v_max3_f32 v128, v80, v64, v81
	v_mfma_f32_32x32x16_bf16 v[0:15], v[116:119], v[32:35], v[0:15]
	ds_read_b128 v[116:119], v154 offset:4096
	v_max3_f32 v172, v65, v82, v66
	v_max3_f32 v128, v83, v67, v128
	v_max3_f32 v172, v84, v68, v172
	v_max3_f32 v128, v85, v69, v128
	v_max3_f32 v172, v86, v70, v172
	v_mfma_f32_32x32x16_bf16 v[16:31], v[120:123], v[40:43], v[16:31]
	ds_read_b128 v[120:123], v155
	v_max3_f32 v128, v87, v71, v128
	v_max3_f32 v172, v88, v72, v172
	v_max3_f32 v128, v89, v73, v128
	v_max3_f32 v172, v90, v74, v172
	v_max3_f32 v128, v91, v75, v128
	v_mfma_f32_32x32x16_bf16 v[0:15], v[124:127], v[40:43], v[0:15]
	ds_read_b128 v[124:127], v155 offset:4096
	v_max3_f32 v172, v92, v76, v172
	v_max3_f32 v128, v93, v77, v128
	v_max3_f32 v172, v94, v78, v172
	v_max3_f32 v128, v95, v79, v128
	v_max_f32_e32 v128, v128, v172
	v_cmp_lt_f32_e32 vcc, s65, v128
	s_cbranch_vccnz .Lgf_rareB

; #define MFMA(a, b, c) __builtin_amdgcn_mfma_f32_32x32x16_bf16((a), (b), (c), 0, 0, 0)
; DI float xhalf(float v) { return __shfl_xor(v, 32); }
;   DI void gload_v(int t) {
;     const u16* vt = Vt + (rowk0 + t * 64);
; #pragma unroll
;     for (int q = 0; q < 2; ++q) rv[q] = ldg16(vt + voff[q]);
;   }
;   template <int PAR>
;   DI void step(int t, f32x16 (&cur)[2], f32x16 (&nxt)[2]) {
;     if (t + 1 < nt) sstore_k(PAR ^ 1);
;     if (t > 0) sstore_v(PAR);
;     __syncthreads();
;     if (t + 1 < nt) qk(PAR ^ 1, nxt);
;     float mx = fmaxf(cur[0][0], cur[1][0]);
; #pragma unroll
;     for (int i = 1; i < 16; ++i) mx = fmaxf(fmaxf(cur[0][i], cur[1][i]), mx);
;     if (__builtin_amdgcn_ballot_w64(mx > ATT_THR) != 0ull) {
;       asm volatile("" ::: "memory");
;       mx = fmaxf(mx, xhalf(mx));
;       const float want = mref + fmaxf(mx, 0.f);
;       const float mn = __uint_as_float(pack2(want, 0.f) << 16);
;       const float d = mn - mref;
;       const float alpha = __builtin_amdgcn_exp2f(-d);
;       mref = mn;
;       l *= alpha;
; #pragma unroll
;       for (int a = 0; a < 2; ++a)
; #pragma unroll
;         for (int i = 0; i < 16; ++i) { o[a][i] *= alpha; cur[a][i] -= d; nxt[a][i] -= d; }
;       u32x4 q4 = {h == 0 ? (pack2(-mn, 0.f) & 0xffffu) : 0u, 0u, 0u, 0u};
;       qm = __builtin_bit_cast(bf16x8, q4);
;     }
;     float psum = 0.f;
; #pragma unroll
;     for (int kb2 = 0; kb2 < 2; ++kb2)
; #pragma unroll
;       for (int i = 0; i < 16; ++i) { const float pv = __builtin_amdgcn_exp2f(cur[kb2][i]); cur[kb2][i] = pv; psum += pv; }
;     l += psum;
;     if (t + 2 < nt) gload_k(t + 2);
;     if (t + 1 < nt) gload_v(t + 1);
;     const u16* vb = sV + PAR * VBUF + r * GP + h * 8;
; #pragma unroll
;     for (int kb2 = 0; kb2 < 2; ++kb2)
; #pragma unroll
;       for (int s2 = 0; s2 < 2; ++s2) {
;         u32x4 pk = {pack2(cur[kb2][8 * s2], cur[kb2][8 * s2 + 1]), pack2(cur[kb2][8 * s2 + 2], cur[kb2][8 * s2 + 3]),
;                     pack2(cur[kb2][8 * s2 + 4], cur[kb2][8 * s2 + 5]), pack2(cur[kb2][8 * s2 + 6], cur[kb2][8 * s2 + 7])};
;         const bf16x8 pf = __builtin_bit_cast(bf16x8, pk);
; #pragma unroll
;         for (int db = 0; db < 2; ++db) {
;           const bf16x8 a = *(const bf16x8*)(vb + db * 32 * GP + kb2 * 32 + s2 * 16);
;           o[db] = MFMA(a, pf, o[db]);
;         }
;       }
;   }
.Lgf_skipKB:
	ds_read_b128 v[96:99], v156 offset:27648
	ds_read_b128 v[100:103], v156 offset:31744
	ds_read_b128 v[104:107], v157 offset:27648
	ds_read_b128 v[108:111], v157 offset:31744
	v_mfma_f32_32x32x16_bf16 v[48:63], v[112:115], v[144:147], v[48:63]
	ds_read_b128 v[112:115], v158 offset:27648
	v_exp_f32_e32 v95, v95
	v_add_f32_e32 v183, v93, v183
	v_cvt_pk_bf16_f32 v88, v88, v89
	v_add_f32_e32 v182, v94, v182
	v_cvt_pk_bf16_f32 v89, v90, v91
	v_add_f32_e32 v183, v95, v183
	v_mfma_f32_32x32x16_bf16 v[32:47], v[116:119], v[144:147], v[32:47]
	ds_read_b128 v[116:119], v158 offset:31744
	v_cvt_pk_bf16_f32 v90, v92, v93
	v_cvt_pk_bf16_f32 v91, v94, v95
	v_exp_f32_e32 v64, v64
	v_exp_f32_e32 v65, v65
	v_exp_f32_e32 v66, v66
	v_add_f32_e32 v182, v64, v182
	v_mfma_f32_32x32x16_bf16 v[48:63], v[120:123], v[148:151], v[48:63]
	ds_read_b128 v[120:123], v159 offset:27648
	v_exp_f32_e32 v67, v67
	v_add_f32_e32 v183, v65, v183
	v_exp_f32_e32 v68, v68
	v_add_f32_e32 v182, v66, v182
	v_exp_f32_e32 v69, v69
	v_add_f32_e32 v183, v67, v183
	s_cmp_ge_u32 s45, s19
	s_cbranch_scc1 .Lgf_lastVB
	s_add_i32 m0, s46, 18432
	s_nop 0
	global_load_lds_dwordx4 v[164:165], off
	global_load_lds_dwordx4 v[166:167], off offset:1024
	v_lshl_add_u64 v[164:165], v[164:165], 0, s[84:85]
	v_lshl_add_u64 v[166:167], v[166:167], 0, s[84:85]
	s_branch .Lgf_skipVB

; #define MFMA(a, b, c) __builtin_amdgcn_mfma_f32_32x32x16_bf16((a), (b), (c), 0, 0, 0)
; DI unsigned pack2(float a, float b) { f32x2v f = {a, b}; bf16x2v v = __builtin_convertvector(f, bf16x2v); return __builtin_bit_cast(unsigned, v); }
; DI float xhalf(float v) { return __shfl_xor(v, 32); }
;   template <int PAR>
;   DI void step(int t, f32x16 (&cur)[2], f32x16 (&nxt)[2]) {
;     if (t + 1 < nt) sstore_k(PAR ^ 1);
;     if (t > 0) sstore_v(PAR);
;     __syncthreads();
;     if (t + 1 < nt) qk(PAR ^ 1, nxt);
;     float mx = fmaxf(cur[0][0], cur[1][0]);
; #pragma unroll
;     for (int i = 1; i < 16; ++i) mx = fmaxf(fmaxf(cur[0][i], cur[1][i]), mx);
;     if (__builtin_amdgcn_ballot_w64(mx > ATT_THR) != 0ull) {
;       asm volatile("" ::: "memory");
;       mx = fmaxf(mx, xhalf(mx));
;       const float want = mref + fmaxf(mx, 0.f);
;       const float mn = __uint_as_float(pack2(want, 0.f) << 16);
;       const float d = mn - mref;
;       const float alpha = __builtin_amdgcn_exp2f(-d);
;       mref = mn;
;       l *= alpha;
; #pragma unroll
;       for (int a = 0; a < 2; ++a)
; #pragma unroll
;         for (int i = 0; i < 16; ++i) { o[a][i] *= alpha; cur[a][i] -= d; nxt[a][i] -= d; }
;       u32x4 q4 = {h == 0 ? (pack2(-mn, 0.f) & 0xffffu) : 0u, 0u, 0u, 0u};
;       qm = __builtin_bit_cast(bf16x8, q4);
;     }
;     float psum = 0.f;
; #pragma unroll
;     for (int kb2 = 0; kb2 < 2; ++kb2)
; #pragma unroll
;       for (int i = 0; i < 16; ++i) { const float pv = __builtin_amdgcn_exp2f(cur[kb2][i]); cur[kb2][i] = pv; psum += pv; }
;     l += psum;
;     if (t + 2 < nt) gload_k(t + 2);
;     if (t + 1 < nt) gload_v(t + 1);
;     const u16* vb = sV + PAR * VBUF + r * GP + h * 8;
; #pragma unroll
;     for (int kb2 = 0; kb2 < 2; ++kb2)
; #pragma unroll
;       for (int s2 = 0; s2 < 2; ++s2) {
;         u32x4 pk = {pack2(cur[kb2][8 * s2], cur[kb2][8 * s2 + 1]), pack2(cur[kb2][8 * s2 + 2], cur[kb2][8 * s2 + 3]),
;                     pack2(cur[kb2][8 * s2 + 4], cur[kb2][8 * s2 + 5]), pack2(cur[kb2][8 * s2 + 6], cur[kb2][8 * s2 + 7])};
;         const bf16x8 pf = __builtin_bit_cast(bf16x8, pk);
; #pragma unroll
;         for (int db = 0; db < 2; ++db) {
;           const bf16x8 a = *(const bf16x8*)(vb + db * 32 * GP + kb2 * 32 + s2 * 16);
;           o[db] = MFMA(a, pf, o[db]);
;         }
;       }
;   }
.Lgf_skipVB:
	v_mfma_f32_32x32x16_bf16 v[32:47], v[124:127], v[148:151], v[32:47]
	ds_read_b128 v[124:127], v159 offset:31744
	v_exp_f32_e32 v70, v70
	v_add_f32_e32 v182, v68, v182
	v_exp_f32_e32 v71, v71
	v_add_f32_e32 v183, v69, v183
	v_cvt_pk_bf16_f32 v64, v64, v65
	v_add_f32_e32 v182, v70, v182
	s_waitcnt lgkmcnt(4)
	v_mfma_f32_32x32x16_bf16 v[16:31], v[96:99], v[80:83], v[16:31]
	ds_read_b128 v[96:99], v152 offset:9216
	v_cvt_pk_bf16_f32 v65, v66, v67
	v_add_f32_e32 v183, v71, v183
	v_cvt_pk_bf16_f32 v66, v68, v69
	v_cvt_pk_bf16_f32 v67, v70, v71
	v_exp_f32_e32 v72, v72
	v_mfma_f32_32x32x16_bf16 v[0:15], v[100:103], v[80:83], v[0:15]
	ds_read_b128 v[100:103], v152 offset:13312
	v_exp_f32_e32 v73, v73
	v_exp_f32_e32 v74, v74
	v_add_f32_e32 v182, v72, v182
	v_exp_f32_e32 v75, v75
	v_add_f32_e32 v183, v73, v183
	v_mfma_f32_32x32x16_bf16 v[16:31], v[104:107], v[88:91], v[16:31]
	ds_read_b128 v[104:107], v153 offset:9216
	v_exp_f32_e32 v76, v76
	v_add_f32_e32 v182, v74, v182
	v_exp_f32_e32 v77, v77
	v_add_f32_e32 v183, v75, v183
	v_exp_f32_e32 v78, v78
	v_mfma_f32_32x32x16_bf16 v[0:15], v[108:111], v[88:91], v[0:15]
	ds_read_b128 v[108:111], v153 offset:13312
	v_add_f32_e32 v182, v76, v182
	v_exp_f32_e32 v79, v79
	v_add_f32_e32 v183, v77, v183
	v_cvt_pk_bf16_f32 v72, v72, v73
	v_add_f32_e32 v182, v78, v182
	s_waitcnt lgkmcnt(4)
	v_mfma_f32_32x32x16_bf16 v[16:31], v[112:115], v[64:67], v[16:31]
	ds_read_b128 v[112:115], v154 offset:9216
	v_cvt_pk_bf16_f32 v73, v74, v75
	v_add_f32_e32 v183, v79, v183
	v_cvt_pk_bf16_f32 v74, v76, v77
	v_cvt_pk_bf16_f32 v75, v78, v79
	v_max3_f32 v128, v48, v32, v49
	v_mfma_f32_32x32x16_bf16 v[0:15], v[116:119], v[64:67], v[0:15]
	ds_read_b128 v[116:119], v154 offset:13312
	v_max3_f32 v172, v33, v50, v34
	v_max3_f32 v128, v51, v35, v128
	v_max3_f32 v172, v52, v36, v172
	v_max3_f32 v128, v53, v37, v128
	v_max3_f32 v172, v54, v38, v172
	v_mfma_f32_32x32x16_bf16 v[16:31], v[120:123], v[72:75], v[16:31]
	ds_read_b128 v[120:123], v155 offset:9216
	v_max3_f32 v128, v55, v39, v128
	v_max3_f32 v172, v56, v40, v172
	v_max3_f32 v128, v57, v41, v128
	v_max3_f32 v172, v58, v42, v172
	v_max3_f32 v128, v59, v43, v128
	v_mfma_f32_32x32x16_bf16 v[0:15], v[124:127], v[72:75], v[0:15]
	ds_read_b128 v[124:127], v155 offset:13312
	v_max3_f32 v172, v60, v44, v172
	v_max3_f32 v128, v61, v45, v128
	v_max3_f32 v172, v62, v46, v172
	v_max3_f32 v128, v63, v47, v128
	v_max_f32_e32 v128, v128, v172
	v_lshl_add_u64 v[130:131], v[130:131], 0, s[84:85]
	v_lshl_add_u64 v[180:181], v[180:181], 0, s[84:85]
	s_mov_b32 s0, s45
	s_add_i32 s45, s45, 2
	s_cmp_lt_u32 s0, s19
	s_cbranch_scc1 .Lgf_top
	s_branch .Lg_fold

;   DI void gload_k(int t) {
;     const int row0 = rowk0 + t * 64;
;     const u16* kt = Kb + (size_t)row0 * kpitch;
;     const u16* pt = KPEb + (size_t)row0 * 32;
; #pragma unroll
;     for (int q = 0; q < NKL; ++q) {
;       const int c = tid + 256 * q, cc = c % KCH;
;       rk[q] = ldg16(((DQK == 96 && cc >= 8) ? pt : kt) + koff[q]);
;     }
;   template <int PAR>
;   DI void step(int t, f32x16 (&cur)[2], f32x16 (&nxt)[2]) {
;     if (t + 1 < nt) sstore_k(PAR ^ 1);
;     if (t > 0) sstore_v(PAR);
;     __syncthreads();
;     if (t + 1 < nt) qk(PAR ^ 1, nxt);
;     float mx = fmaxf(cur[0][0], cur[1][0]);
; #pragma unroll
;     for (int i = 1; i < 16; ++i) mx = fmaxf(fmaxf(cur[0][i], cur[1][i]), mx);
;     if (__builtin_amdgcn_ballot_w64(mx > ATT_THR) != 0ull) {
;       asm volatile("" ::: "memory");
;       mx = fmaxf(mx, xhalf(mx));
;       const float want = mref + fmaxf(mx, 0.f);
;       const float mn = __uint_as_float(pack2(want, 0.f) << 16);
;       const float d = mn - mref;
;       const float alpha = __builtin_amdgcn_exp2f(-d);
;       mref = mn;
;       l *= alpha;
; #pragma unroll
;       for (int a = 0; a < 2; ++a)
; #pragma unroll
;         for (int i = 0; i < 16; ++i) { o[a][i] *= alpha; cur[a][i] -= d; nxt[a][i] -= d; }
;       u32x4 q4 = {h == 0 ? (pack2(-mn, 0.f) & 0xffffu) : 0u, 0u, 0u, 0u};
;       qm = __builtin_bit_cast(bf16x8, q4);
;     }
;     float psum = 0.f;
; #pragma unroll
;     for (int kb2 = 0; kb2 < 2; ++kb2)
; #pragma unroll
;       for (int i = 0; i < 16; ++i) { const float pv = __builtin_amdgcn_exp2f(cur[kb2][i]); cur[kb2][i] = pv; psum += pv; }
;     l += psum;
;     if (t + 2 < nt) gload_k(t + 2);
;     if (t + 1 < nt) gload_v(t + 1);
;     const u16* vb = sV + PAR * VBUF + r * GP + h * 8;
; #pragma unroll
;     for (int kb2 = 0; kb2 < 2; ++kb2)
; #pragma unroll
;       for (int s2 = 0; s2 < 2; ++s2) {
;         u32x4 pk = {pack2(cur[kb2][8 * s2], cur[kb2][8 * s2 + 1]), pack2(cur[kb2][8 * s2 + 2], cur[kb2][8 * s2 + 3]),
;                     pack2(cur[kb2][8 * s2 + 4], cur[kb2][8 * s2 + 5]), pack2(cur[kb2][8 * s2 + 6], cur[kb2][8 * s2 + 7])};
;         const bf16x8 pf = __builtin_bit_cast(bf16x8, pk);
; #pragma unroll
;         for (int db = 0; db < 2; ++db) {
;           const bf16x8 a = *(const bf16x8*)(vb + db * 32 * GP + kb2 * 32 + s2 * 16);
;           o[db] = MFMA(a, pf, o[db]);
;         }
;       }
;   }
.Lg_skipKA:
	ds_read_b128 v[96:99], v156 offset:18432
	ds_read_b128 v[100:103], v156 offset:22528
	ds_read_b128 v[104:107], v157 offset:18432
	ds_read_b128 v[108:111], v157 offset:22528
	v_mfma_f32_32x32x16_bf16 v[80:95], v[112:115], v[144:147], v[80:95]
	ds_read_b128 v[112:115], v158 offset:18432
	v_exp_f32_e32 v61, v61
	v_add_f32_e32 v183, v59, v183
	v_exp_f32_e32 v62, v62
	v_add_f32_e32 v182, v60, v182
	v_exp_f32_e32 v63, v63
	v_mfma_f32_32x32x16_bf16 v[64:79], v[116:119], v[144:147], v[64:79]
	ds_read_b128 v[116:119], v158 offset:22528
	v_add_f32_e32 v183, v61, v183
	v_cvt_pk_bf16_f32 v56, v56, v57
	v_add_f32_e32 v182, v62, v182
	v_cvt_pk_bf16_f32 v57, v58, v59
	v_add_f32_e32 v183, v63, v183
	v_mfma_f32_32x32x16_bf16 v[80:95], v[120:123], v[148:151], v[80:95]
	ds_read_b128 v[120:123], v159 offset:18432
	v_cvt_pk_bf16_f32 v58, v60, v61
	v_cvt_pk_bf16_f32 v59, v62, v63
	v_exp_f32_e32 v32, v32
	v_exp_f32_e32 v33, v33
	v_exp_f32_e32 v34, v34
	s_add_i32 m0, s46, 27648
	s_nop 0
	global_load_lds_dwordx4 v[160:161], off
	global_load_lds_dwordx4 v[162:163], off offset:1024
	v_lshl_add_u64 v[160:161], v[160:161], 0, s[84:85]
	v_lshl_add_u64 v[162:163], v[162:163], 0, s[84:85]
	v_mfma_f32_32x32x16_bf16 v[64:79], v[124:127], v[148:151], v[64:79]
	ds_read_b128 v[124:127], v159 offset:22528
	v_add_f32_e32 v182, v32, v182
	v_exp_f32_e32 v35, v35
	v_add_f32_e32 v183, v33, v183
	v_exp_f32_e32 v36, v36
	v_add_f32_e32 v182, v34, v182
	v_mfma_f32_32x32x16_bf16 v[80:95], v[132:135], v[168:171], v[80:95]
	v_exp_f32_e32 v37, v37
	v_add_f32_e32 v183, v35, v183
	v_exp_f32_e32 v38, v38
	v_add_f32_e32 v182, v36, v182
	v_exp_f32_e32 v39, v39
	v_mfma_f32_32x32x16_bf16 v[64:79], v[132:135], v[168:171], v[64:79]
	v_add_f32_e32 v183, v37, v183
	v_cvt_pk_bf16_f32 v32, v32, v33
	v_add_f32_e32 v182, v38, v182
	v_cvt_pk_bf16_f32 v33, v34, v35
	v_add_f32_e32 v183, v39, v183
	s_waitcnt lgkmcnt(4)
	v_mfma_f32_32x32x16_bf16 v[16:31], v[96:99], v[48:51], v[16:31]
	ds_read_b128 v[96:99], v152
	v_cvt_pk_bf16_f32 v34, v36, v37
	v_cvt_pk_bf16_f32 v35, v38, v39
	v_exp_f32_e32 v40, v40
	v_exp_f32_e32 v41, v41
	v_exp_f32_e32 v42, v42
	v_mfma_f32_32x32x16_bf16 v[0:15], v[100:103], v[48:51], v[0:15]
	ds_read_b128 v[100:103], v152 offset:4096
	v_add_f32_e32 v182, v40, v182
	v_exp_f32_e32 v43, v43
	v_add_f32_e32 v183, v41, v183
	v_exp_f32_e32 v44, v44
	v_add_f32_e32 v182, v42, v182
	v_mfma_f32_32x32x16_bf16 v[16:31], v[104:107], v[56:59], v[16:31]
	ds_read_b128 v[104:107], v153
	v_exp_f32_e32 v45, v45
	v_add_f32_e32 v183, v43, v183
	v_exp_f32_e32 v46, v46
	v_add_f32_e32 v182, v44, v182
	v_exp_f32_e32 v47, v47
	v_mfma_f32_32x32x16_bf16 v[0:15], v[108:111], v[56:59], v[0:15]
	ds_read_b128 v[108:111], v153 offset:4096
	v_add_f32_e32 v183, v45, v183
	v_cvt_pk_bf16_f32 v40, v40, v41
	v_add_f32_e32 v182, v46, v182
	v_cvt_pk_bf16_f32 v41, v42, v43
	v_add_f32_e32 v183, v47, v183
	s_waitcnt lgkmcnt(4)
	v_mfma_f32_32x32x16_bf16 v[16:31], v[112:115], v[32:35], v[16:31]
	ds_read_b128 v[112:115], v154
	v_cvt_pk_bf16_f32 v42, v44, v45
	v_cvt_pk_bf16_f32 v43, v46, v47
	v_max3_f32 v128, v80, v64, v81
	v_max3_f32 v172, v65, v82, v66
	v_max3_f32 v128, v83, v67, v128
	v_mfma_f32_32x32x16_bf16 v[0:15], v[116:119], v[32:35], v[0:15]
	ds_read_b128 v[116:119], v154 offset:4096
	v_max3_f32 v172, v84, v68, v172
	v_max3_f32 v128, v85, v69, v128
	v_max3_f32 v172, v86, v70, v172
	v_max3_f32 v128, v87, v71, v128
	v_max3_f32 v172, v88, v72, v172
	v_mfma_f32_32x32x16_bf16 v[16:31], v[120:123], v[40:43], v[16:31]
	ds_read_b128 v[120:123], v155
	v_max3_f32 v128, v89, v73, v128
	v_max3_f32 v172, v90, v74, v172
	v_max3_f32 v128, v91, v75, v128
	v_max3_f32 v172, v92, v76, v172
	v_mfma_f32_32x32x16_bf16 v[0:15], v[124:127], v[40:43], v[0:15]
	ds_read_b128 v[124:127], v155 offset:4096
	v_max3_f32 v128, v93, v77, v128
	v_max3_f32 v172, v94, v78, v172
	v_max3_f32 v128, v95, v79, v128
	v_max_f32_e32 v128, v128, v172
	v_cmp_lt_f32_e32 vcc, s65, v128
	s_cbranch_vccnz .Lg_rareB

; #define MFMA(a, b, c) __builtin_amdgcn_mfma_f32_32x32x16_bf16((a), (b), (c), 0, 0, 0)
; DI float xhalf(float v) { return __shfl_xor(v, 32); }
;   DI void gload_v(int t) {
;     const u16* vt = Vt + (rowk0 + t * 64);
; #pragma unroll
;     for (int q = 0; q < 2; ++q) rv[q] = ldg16(vt + voff[q]);
;   }
;   template <int PAR>
;   DI void step(int t, f32x16 (&cur)[2], f32x16 (&nxt)[2]) {
;     if (t + 1 < nt) sstore_k(PAR ^ 1);
;     if (t > 0) sstore_v(PAR);
;     __syncthreads();
;     if (t + 1 < nt) qk(PAR ^ 1, nxt);
;     float mx = fmaxf(cur[0][0], cur[1][0]);
; #pragma unroll
;     for (int i = 1; i < 16; ++i) mx = fmaxf(fmaxf(cur[0][i], cur[1][i]), mx);
;     if (__builtin_amdgcn_ballot_w64(mx > ATT_THR) != 0ull) {
;       asm volatile("" ::: "memory");
;       mx = fmaxf(mx, xhalf(mx));
;       const float want = mref + fmaxf(mx, 0.f);
;       const float mn = __uint_as_float(pack2(want, 0.f) << 16);
;       const float d = mn - mref;
;       const float alpha = __builtin_amdgcn_exp2f(-d);
;       mref = mn;
;       l *= alpha;
; #pragma unroll
;       for (int a = 0; a < 2; ++a)
; #pragma unroll
;         for (int i = 0; i < 16; ++i) { o[a][i] *= alpha; cur[a][i] -= d; nxt[a][i] -= d; }
;       u32x4 q4 = {h == 0 ? (pack2(-mn, 0.f) & 0xffffu) : 0u, 0u, 0u, 0u};
;       qm = __builtin_bit_cast(bf16x8, q4);
;     }
;     float psum = 0.f;
; #pragma unroll
;     for (int kb2 = 0; kb2 < 2; ++kb2)
; #pragma unroll
;       for (int i = 0; i < 16; ++i) { const float pv = __builtin_amdgcn_exp2f(cur[kb2][i]); cur[kb2][i] = pv; psum += pv; }
;     l += psum;
;     if (t + 2 < nt) gload_k(t + 2);
;     if (t + 1 < nt) gload_v(t + 1);
;     const u16* vb = sV + PAR * VBUF + r * GP + h * 8;
; #pragma unroll
;     for (int kb2 = 0; kb2 < 2; ++kb2)
; #pragma unroll
;       for (int s2 = 0; s2 < 2; ++s2) {
;         u32x4 pk = {pack2(cur[kb2][8 * s2], cur[kb2][8 * s2 + 1]), pack2(cur[kb2][8 * s2 + 2], cur[kb2][8 * s2 + 3]),
;                     pack2(cur[kb2][8 * s2 + 4], cur[kb2][8 * s2 + 5]), pack2(cur[kb2][8 * s2 + 6], cur[kb2][8 * s2 + 7])};
;         const bf16x8 pf = __builtin_bit_cast(bf16x8, pk);
; #pragma unroll
;         for (int db = 0; db < 2; ++db) {
;           const bf16x8 a = *(const bf16x8*)(vb + db * 32 * GP + kb2 * 32 + s2 * 16);
;           o[db] = MFMA(a, pf, o[db]);
;         }
;       }
;   }
.Lg_skipKB:
	ds_read_b128 v[96:99], v156 offset:27648
	ds_read_b128 v[100:103], v156 offset:31744
	ds_read_b128 v[104:107], v157 offset:27648
	ds_read_b128 v[108:111], v157 offset:31744
	v_mfma_f32_32x32x16_bf16 v[48:63], v[112:115], v[144:147], v[48:63]
	ds_read_b128 v[112:115], v158 offset:27648
	v_exp_f32_e32 v93, v93
	v_add_f32_e32 v183, v91, v183
	v_exp_f32_e32 v94, v94
	v_add_f32_e32 v182, v92, v182
	v_exp_f32_e32 v95, v95
	v_mfma_f32_32x32x16_bf16 v[32:47], v[116:119], v[144:147], v[32:47]
	ds_read_b128 v[116:119], v158 offset:31744
	v_add_f32_e32 v183, v93, v183
	v_cvt_pk_bf16_f32 v88, v88, v89
	v_add_f32_e32 v182, v94, v182
	v_cvt_pk_bf16_f32 v89, v90, v91
	v_add_f32_e32 v183, v95, v183
	v_mfma_f32_32x32x16_bf16 v[48:63], v[120:123], v[148:151], v[48:63]
	ds_read_b128 v[120:123], v159 offset:27648
	v_cvt_pk_bf16_f32 v90, v92, v93
	v_cvt_pk_bf16_f32 v91, v94, v95
	v_exp_f32_e32 v64, v64
	v_exp_f32_e32 v65, v65
	v_exp_f32_e32 v66, v66
	s_cmp_ge_u32 s45, s19
	s_cbranch_scc1 .Lg_lastVB
	s_add_i32 m0, s46, 18432
	s_nop 0
	global_load_lds_dwordx4 v[164:165], off
	global_load_lds_dwordx4 v[166:167], off offset:1024
	v_lshl_add_u64 v[164:165], v[164:165], 0, s[84:85]
	v_lshl_add_u64 v[166:167], v[166:167], 0, s[84:85]
	s_branch .Lg_skipVB

; #define MFMA(a, b, c) __builtin_amdgcn_mfma_f32_32x32x16_bf16((a), (b), (c), 0, 0, 0)
; DI unsigned pack2(float a, float b) { f32x2v f = {a, b}; bf16x2v v = __builtin_convertvector(f, bf16x2v); return __builtin_bit_cast(unsigned, v); }
; DI float xhalf(float v) { return __shfl_xor(v, 32); }
;   template <int PAR>
;   DI void step(int t, f32x16 (&cur)[2], f32x16 (&nxt)[2]) {
;     if (t + 1 < nt) sstore_k(PAR ^ 1);
;     if (t > 0) sstore_v(PAR);
;     __syncthreads();
;     if (t + 1 < nt) qk(PAR ^ 1, nxt);
;     float mx = fmaxf(cur[0][0], cur[1][0]);
; #pragma unroll
;     for (int i = 1; i < 16; ++i) mx = fmaxf(fmaxf(cur[0][i], cur[1][i]), mx);
;     if (__builtin_amdgcn_ballot_w64(mx > ATT_THR) != 0ull) {
;       asm volatile("" ::: "memory");
;       mx = fmaxf(mx, xhalf(mx));
;       const float want = mref + fmaxf(mx, 0.f);
;       const float mn = __uint_as_float(pack2(want, 0.f) << 16);
;       const float d = mn - mref;
;       const float alpha = __builtin_amdgcn_exp2f(-d);
;       mref = mn;
;       l *= alpha;
; #pragma unroll
;       for (int a = 0; a < 2; ++a)
; #pragma unroll
;         for (int i = 0; i < 16; ++i) { o[a][i] *= alpha; cur[a][i] -= d; nxt[a][i] -= d; }
;       u32x4 q4 = {h == 0 ? (pack2(-mn, 0.f) & 0xffffu) : 0u, 0u, 0u, 0u};
;       qm = __builtin_bit_cast(bf16x8, q4);
;     }
;     float psum = 0.f;
; #pragma unroll
;     for (int kb2 = 0; kb2 < 2; ++kb2)
; #pragma unroll
;       for (int i = 0; i < 16; ++i) { const float pv = __builtin_amdgcn_exp2f(cur[kb2][i]); cur[kb2][i] = pv; psum += pv; }
;     l += psum;
;     if (t + 2 < nt) gload_k(t + 2);
;     if (t + 1 < nt) gload_v(t + 1);
;     const u16* vb = sV + PAR * VBUF + r * GP + h * 8;
; #pragma unroll
;     for (int kb2 = 0; kb2 < 2; ++kb2)
; #pragma unroll
;       for (int s2 = 0; s2 < 2; ++s2) {
;         u32x4 pk = {pack2(cur[kb2][8 * s2], cur[kb2][8 * s2 + 1]), pack2(cur[kb2][8 * s2 + 2], cur[kb2][8 * s2 + 3]),
;                     pack2(cur[kb2][8 * s2 + 4], cur[kb2][8 * s2 + 5]), pack2(cur[kb2][8 * s2 + 6], cur[kb2][8 * s2 + 7])};
;         const bf16x8 pf = __builtin_bit_cast(bf16x8, pk);
; #pragma unroll
;         for (int db = 0; db < 2; ++db) {
;           const bf16x8 a = *(const bf16x8*)(vb + db * 32 * GP + kb2 * 32 + s2 * 16);
;           o[db] = MFMA(a, pf, o[db]);
;         }
;       }
;   }
.Lg_skipVB:
	v_mfma_f32_32x32x16_bf16 v[32:47], v[124:127], v[148:151], v[32:47]
	ds_read_b128 v[124:127], v159 offset:31744
	v_add_f32_e32 v182, v64, v182
	v_exp_f32_e32 v67, v67
	v_add_f32_e32 v183, v65, v183
	v_exp_f32_e32 v68, v68
	v_add_f32_e32 v182, v66, v182
	v_mfma_f32_32x32x16_bf16 v[48:63], v[132:135], v[168:171], v[48:63]
	v_exp_f32_e32 v69, v69
	v_add_f32_e32 v183, v67, v183
	v_exp_f32_e32 v70, v70
	v_add_f32_e32 v182, v68, v182
	v_exp_f32_e32 v71, v71
	v_mfma_f32_32x32x16_bf16 v[32:47], v[132:135], v[168:171], v[32:47]
	v_add_f32_e32 v183, v69, v183
	v_cvt_pk_bf16_f32 v64, v64, v65
	v_add_f32_e32 v182, v70, v182
	v_cvt_pk_bf16_f32 v65, v66, v67
	v_add_f32_e32 v183, v71, v183
	s_waitcnt lgkmcnt(4)
	v_mfma_f32_32x32x16_bf16 v[16:31], v[96:99], v[80:83], v[16:31]
	ds_read_b128 v[96:99], v152 offset:9216
	v_cvt_pk_bf16_f32 v66, v68, v69
	v_cvt_pk_bf16_f32 v67, v70, v71
	v_exp_f32_e32 v72, v72
	v_exp_f32_e32 v73, v73
	v_exp_f32_e32 v74, v74
	v_mfma_f32_32x32x16_bf16 v[0:15], v[100:103], v[80:83], v[0:15]
	ds_read_b128 v[100:103], v152 offset:13312
	v_add_f32_e32 v182, v72, v182
	v_exp_f32_e32 v75, v75
	v_add_f32_e32 v183, v73, v183
	v_exp_f32_e32 v76, v76
	v_add_f32_e32 v182, v74, v182
	v_mfma_f32_32x32x16_bf16 v[16:31], v[104:107], v[88:91], v[16:31]
	ds_read_b128 v[104:107], v153 offset:9216
	v_exp_f32_e32 v77, v77
	v_add_f32_e32 v183, v75, v183
	v_exp_f32_e32 v78, v78
	v_add_f32_e32 v182, v76, v182
	v_exp_f32_e32 v79, v79
	v_mfma_f32_32x32x16_bf16 v[0:15], v[108:111], v[88:91], v[0:15]
	ds_read_b128 v[108:111], v153 offset:13312
	v_add_f32_e32 v183, v77, v183
	v_cvt_pk_bf16_f32 v72, v72, v73
	v_add_f32_e32 v182, v78, v182
	v_cvt_pk_bf16_f32 v73, v74, v75
	v_add_f32_e32 v183, v79, v183
	s_waitcnt lgkmcnt(4)
	v_mfma_f32_32x32x16_bf16 v[16:31], v[112:115], v[64:67], v[16:31]
	ds_read_b128 v[112:115], v154 offset:9216
	v_cvt_pk_bf16_f32 v74, v76, v77
	v_cvt_pk_bf16_f32 v75, v78, v79
	v_max3_f32 v128, v48, v32, v49
	v_max3_f32 v172, v33, v50, v34
	v_max3_f32 v128, v51, v35, v128
	v_mfma_f32_32x32x16_bf16 v[0:15], v[116:119], v[64:67], v[0:15]
	ds_read_b128 v[116:119], v154 offset:13312
	v_max3_f32 v172, v52, v36, v172
	v_max3_f32 v128, v53, v37, v128
	v_max3_f32 v172, v54, v38, v172
	v_max3_f32 v128, v55, v39, v128
	v_max3_f32 v172, v56, v40, v172
	v_mfma_f32_32x32x16_bf16 v[16:31], v[120:123], v[72:75], v[16:31]
	ds_read_b128 v[120:123], v155 offset:9216
	v_max3_f32 v128, v57, v41, v128
	v_max3_f32 v172, v58, v42, v172
	v_max3_f32 v128, v59, v43, v128
	v_max3_f32 v172, v60, v44, v172
	v_mfma_f32_32x32x16_bf16 v[0:15], v[124:127], v[72:75], v[0:15]
	ds_read_b128 v[124:127], v155 offset:13312
	v_max3_f32 v128, v61, v45, v128
	v_max3_f32 v172, v62, v46, v172
	v_max3_f32 v128, v63, v47, v128
	v_max_f32_e32 v128, v128, v172
	v_lshl_add_u64 v[130:131], v[130:131], 0, s[84:85]
	v_lshl_add_u64 v[180:181], v[180:181], 0, s[84:85]
	s_mov_b32 s0, s45
	s_add_i32 s45, s45, 2
	s_cmp_lt_u32 s0, s19
	s_cbranch_scc1 .LBB0_238
	s_branch .Lg_fold

;   DI void gload_k(int t) {
;     const int row0 = rowk0 + t * 64;
;     const u16* kt = Kb + (size_t)row0 * kpitch;
;     const u16* pt = KPEb + (size_t)row0 * 32;
; #pragma unroll
;     for (int q = 0; q < NKL; ++q) {
;       const int c = tid + 256 * q, cc = c % KCH;
;       rk[q] = ldg16(((DQK == 96 && cc >= 8) ? pt : kt) + koff[q]);
;     }
;   template <int PAR>
;   DI void step(int t, f32x16 (&cur)[2], f32x16 (&nxt)[2]) {
;     if (t + 1 < nt) sstore_k(PAR ^ 1);
;     if (t > 0) sstore_v(PAR);
;     __syncthreads();
;     if (t + 1 < nt) qk(PAR ^ 1, nxt);
;     float mx = fmaxf(cur[0][0], cur[1][0]);
; #pragma unroll
;     for (int i = 1; i < 16; ++i) mx = fmaxf(fmaxf(cur[0][i], cur[1][i]), mx);
;     if (__builtin_amdgcn_ballot_w64(mx > ATT_THR) != 0ull) {
;       asm volatile("" ::: "memory");
;       mx = fmaxf(mx, xhalf(mx));
;       const float want = mref + fmaxf(mx, 0.f);
;       const float mn = __uint_as_float(pack2(want, 0.f) << 16);
;       const float d = mn - mref;
;       const float alpha = __builtin_amdgcn_exp2f(-d);
;       mref = mn;
;       l *= alpha;
; #pragma unroll
;       for (int a = 0; a < 2; ++a)
; #pragma unroll
;         for (int i = 0; i < 16; ++i) { o[a][i] *= alpha; cur[a][i] -= d; nxt[a][i] -= d; }
;       u32x4 q4 = {h == 0 ? (pack2(-mn, 0.f) & 0xffffu) : 0u, 0u, 0u, 0u};
;       qm = __builtin_bit_cast(bf16x8, q4);
;     }
;     float psum = 0.f;
; #pragma unroll
;     for (int kb2 = 0; kb2 < 2; ++kb2)
; #pragma unroll
;       for (int i = 0; i < 16; ++i) { const float pv = __builtin_amdgcn_exp2f(cur[kb2][i]); cur[kb2][i] = pv; psum += pv; }
;     l += psum;
;     if (t + 2 < nt) gload_k(t + 2);
;     if (t + 1 < nt) gload_v(t + 1);
;     const u16* vb = sV + PAR * VBUF + r * GP + h * 8;
; #pragma unroll
;     for (int kb2 = 0; kb2 < 2; ++kb2)
; #pragma unroll
;       for (int s2 = 0; s2 < 2; ++s2) {
;         u32x4 pk = {pack2(cur[kb2][8 * s2], cur[kb2][8 * s2 + 1]), pack2(cur[kb2][8 * s2 + 2], cur[kb2][8 * s2 + 3]),
;                     pack2(cur[kb2][8 * s2 + 4], cur[kb2][8 * s2 + 5]), pack2(cur[kb2][8 * s2 + 6], cur[kb2][8 * s2 + 7])};
;         const bf16x8 pf = __builtin_bit_cast(bf16x8, pk);
; #pragma unroll
;         for (int db = 0; db < 2; ++db) {
;           const bf16x8 a = *(const bf16x8*)(vb + db * 32 * GP + kb2 * 32 + s2 * 16);
;           o[db] = MFMA(a, pf, o[db]);
;         }
;       }
;   }
.Lmf_skipKA:
	v_mfma_f32_32x32x16_bf16 v[80:95], v[112:115], v[144:147], v[80:95]
	ds_read_b128 v[112:115], v166 offset:25600
	v_exp_f32_e32 v61, v61
	v_add_f32_e32 v239, v59, v239
	v_exp_f32_e32 v62, v62
	v_add_f32_e32 v238, v60, v238
	v_exp_f32_e32 v63, v63
	v_mfma_f32_32x32x16_bf16 v[64:79], v[116:119], v[144:147], v[64:79]
	ds_read_b128 v[116:119], v166 offset:29696
	v_add_f32_e32 v239, v61, v239
	v_cvt_pk_bf16_f32 v56, v56, v57
	v_add_f32_e32 v238, v62, v238
	v_cvt_pk_bf16_f32 v57, v58, v59
	v_add_f32_e32 v239, v63, v239
	v_mfma_f32_32x32x16_bf16 v[80:95], v[120:123], v[148:151], v[80:95]
	ds_read_b128 v[120:123], v167 offset:25600
	v_cvt_pk_bf16_f32 v58, v60, v61
	v_cvt_pk_bf16_f32 v59, v62, v63
	v_exp_f32_e32 v32, v32
	v_exp_f32_e32 v33, v33
	v_exp_f32_e32 v34, v34
	s_add_i32 m0, s44, 36864
	s_nop 0
	global_load_lds_dwordx4 v[176:177], off
	global_load_lds_dwordx4 v[178:179], off offset:1024
	v_mfma_f32_32x32x16_bf16 v[64:79], v[124:127], v[148:151], v[64:79]
	ds_read_b128 v[124:127], v167 offset:29696
	v_add_f32_e32 v238, v32, v238
	v_exp_f32_e32 v35, v35
	v_add_f32_e32 v239, v33, v239
	v_exp_f32_e32 v36, v36
	v_add_f32_e32 v238, v34, v238
	v_mfma_f32_32x32x16_bf16 v[80:95], v[96:99], v[152:155], v[80:95]
	ds_read_b128 v[96:99], v168 offset:25600
	v_exp_f32_e32 v37, v37
	v_add_f32_e32 v239, v35, v239
	v_exp_f32_e32 v38, v38
	v_add_f32_e32 v238, v36, v238
	v_mfma_f32_32x32x16_bf16 v[64:79], v[100:103], v[152:155], v[64:79]
	ds_read_b128 v[100:103], v168 offset:29696
	v_exp_f32_e32 v39, v39
	v_add_f32_e32 v239, v37, v239
	v_cvt_pk_bf16_f32 v32, v32, v33
	v_add_f32_e32 v238, v38, v238
	v_mfma_f32_32x32x16_bf16 v[80:95], v[104:107], v[156:159], v[80:95]
	ds_read_b128 v[104:107], v169 offset:25600
	v_cvt_pk_bf16_f32 v33, v34, v35
	v_add_f32_e32 v239, v39, v239
	v_cvt_pk_bf16_f32 v34, v36, v37
	v_cvt_pk_bf16_f32 v35, v38, v39
	v_mfma_f32_32x32x16_bf16 v[64:79], v[108:111], v[156:159], v[64:79]
	ds_read_b128 v[108:111], v169 offset:29696
	v_exp_f32_e32 v40, v40
	v_exp_f32_e32 v41, v41
	v_exp_f32_e32 v42, v42
	v_add_f32_e32 v238, v40, v238
	s_waitcnt lgkmcnt(4)
	v_mfma_f32_32x32x16_bf16 v[16:31], v[112:115], v[48:51], v[16:31]
	ds_read_b128 v[112:115], v162
	v_exp_f32_e32 v43, v43
	v_add_f32_e32 v239, v41, v239
	v_exp_f32_e32 v44, v44
	v_add_f32_e32 v238, v42, v238
	v_mfma_f32_32x32x16_bf16 v[0:15], v[116:119], v[48:51], v[0:15]
	ds_read_b128 v[116:119], v162 offset:4096
	v_exp_f32_e32 v45, v45
	v_add_f32_e32 v239, v43, v239
	v_exp_f32_e32 v46, v46
	v_add_f32_e32 v238, v44, v238
	v_mfma_f32_32x32x16_bf16 v[16:31], v[120:123], v[56:59], v[16:31]
	ds_read_b128 v[120:123], v163
	v_exp_f32_e32 v47, v47
	v_add_f32_e32 v239, v45, v239
	v_cvt_pk_bf16_f32 v40, v40, v41
	v_add_f32_e32 v238, v46, v238
	v_mfma_f32_32x32x16_bf16 v[0:15], v[124:127], v[56:59], v[0:15]
	ds_read_b128 v[124:127], v163 offset:4096
	v_cvt_pk_bf16_f32 v41, v42, v43
	v_add_f32_e32 v239, v47, v239
	v_cvt_pk_bf16_f32 v42, v44, v45
	v_cvt_pk_bf16_f32 v43, v46, v47
	s_waitcnt lgkmcnt(4)
	v_mfma_f32_32x32x16_bf16 v[16:31], v[96:99], v[32:35], v[16:31]
	ds_read_b128 v[96:99], v160
	v_max3_f32 v240, v80, v64, v81
	v_max3_f32 v241, v65, v82, v66
	v_max3_f32 v240, v83, v67, v240
	v_max3_f32 v241, v84, v68, v241
	v_mfma_f32_32x32x16_bf16 v[0:15], v[100:103], v[32:35], v[0:15]
	ds_read_b128 v[100:103], v160 offset:4096
	v_max3_f32 v240, v85, v69, v240
	v_max3_f32 v241, v86, v70, v241
	v_max3_f32 v240, v87, v71, v240
	v_max3_f32 v241, v88, v72, v241
	v_mfma_f32_32x32x16_bf16 v[16:31], v[104:107], v[40:43], v[16:31]
	ds_read_b128 v[104:107], v161
	v_max3_f32 v240, v89, v73, v240
	v_max3_f32 v241, v90, v74, v241
	v_max3_f32 v240, v91, v75, v240
	v_max3_f32 v241, v92, v76, v241
	v_mfma_f32_32x32x16_bf16 v[0:15], v[108:111], v[40:43], v[0:15]
	ds_read_b128 v[108:111], v161 offset:4096
	v_max3_f32 v240, v93, v77, v240
	v_max3_f32 v241, v94, v78, v241
	v_max3_f32 v240, v95, v79, v240
	v_max_f32_e32 v240, v240, v241
	v_cmp_lt_f32_e32 vcc, s65, v240
	s_cbranch_vccnz .Lmf_rareB

; #define MFMA(a, b, c) __builtin_amdgcn_mfma_f32_32x32x16_bf16((a), (b), (c), 0, 0, 0)
; DI float xhalf(float v) { return __shfl_xor(v, 32); }
;   DI void gload_v(int t) {
;     const u16* vt = Vt + (rowk0 + t * 64);
; #pragma unroll
;     for (int q = 0; q < 2; ++q) rv[q] = ldg16(vt + voff[q]);
;   }
;   template <int PAR>
;   DI void step(int t, f32x16 (&cur)[2], f32x16 (&nxt)[2]) {
;     if (t + 1 < nt) sstore_k(PAR ^ 1);
;     if (t > 0) sstore_v(PAR);
;     __syncthreads();
;     if (t + 1 < nt) qk(PAR ^ 1, nxt);
;     float mx = fmaxf(cur[0][0], cur[1][0]);
; #pragma unroll
;     for (int i = 1; i < 16; ++i) mx = fmaxf(fmaxf(cur[0][i], cur[1][i]), mx);
;     if (__builtin_amdgcn_ballot_w64(mx > ATT_THR) != 0ull) {
;       asm volatile("" ::: "memory");
;       mx = fmaxf(mx, xhalf(mx));
;       const float want = mref + fmaxf(mx, 0.f);
;       const float mn = __uint_as_float(pack2(want, 0.f) << 16);
;       const float d = mn - mref;
;       const float alpha = __builtin_amdgcn_exp2f(-d);
;       mref = mn;
;       l *= alpha;
; #pragma unroll
;       for (int a = 0; a < 2; ++a)
; #pragma unroll
;         for (int i = 0; i < 16; ++i) { o[a][i] *= alpha; cur[a][i] -= d; nxt[a][i] -= d; }
;       u32x4 q4 = {h == 0 ? (pack2(-mn, 0.f) & 0xffffu) : 0u, 0u, 0u, 0u};
;       qm = __builtin_bit_cast(bf16x8, q4);
;     }
;     float psum = 0.f;
; #pragma unroll
;     for (int kb2 = 0; kb2 < 2; ++kb2)
; #pragma unroll
;       for (int i = 0; i < 16; ++i) { const float pv = __builtin_amdgcn_exp2f(cur[kb2][i]); cur[kb2][i] = pv; psum += pv; }
;     l += psum;
;     if (t + 2 < nt) gload_k(t + 2);
;     if (t + 1 < nt) gload_v(t + 1);
;     const u16* vb = sV + PAR * VBUF + r * GP + h * 8;
; #pragma unroll
;     for (int kb2 = 0; kb2 < 2; ++kb2)
; #pragma unroll
;       for (int s2 = 0; s2 < 2; ++s2) {
;         u32x4 pk = {pack2(cur[kb2][8 * s2], cur[kb2][8 * s2 + 1]), pack2(cur[kb2][8 * s2 + 2], cur[kb2][8 * s2 + 3]),
;                     pack2(cur[kb2][8 * s2 + 4], cur[kb2][8 * s2 + 5]), pack2(cur[kb2][8 * s2 + 6], cur[kb2][8 * s2 + 7])};
;         const bf16x8 pf = __builtin_bit_cast(bf16x8, pk);
; #pragma unroll
;         for (int db = 0; db < 2; ++db) {
;           const bf16x8 a = *(const bf16x8*)(vb + db * 32 * GP + kb2 * 32 + s2 * 16);
;           o[db] = MFMA(a, pf, o[db]);
;         }
;       }
;   }
.Lmf_skipKB:
	v_mfma_f32_32x32x16_bf16 v[48:63], v[112:115], v[144:147], v[48:63]
	ds_read_b128 v[112:115], v166 offset:36864
	v_exp_f32_e32 v93, v93
	v_add_f32_e32 v239, v91, v239
	v_exp_f32_e32 v94, v94
	v_add_f32_e32 v238, v92, v238
	v_exp_f32_e32 v95, v95
	v_mfma_f32_32x32x16_bf16 v[32:47], v[116:119], v[144:147], v[32:47]
	ds_read_b128 v[116:119], v166 offset:40960
	v_add_f32_e32 v239, v93, v239
	v_cvt_pk_bf16_f32 v88, v88, v89
	v_add_f32_e32 v238, v94, v238
	v_cvt_pk_bf16_f32 v89, v90, v91
	v_add_f32_e32 v239, v95, v239
	v_mfma_f32_32x32x16_bf16 v[48:63], v[120:123], v[148:151], v[48:63]
	ds_read_b128 v[120:123], v167 offset:36864
	v_cvt_pk_bf16_f32 v90, v92, v93
	v_cvt_pk_bf16_f32 v91, v94, v95
	v_exp_f32_e32 v64, v64
	v_exp_f32_e32 v65, v65
	v_exp_f32_e32 v66, v66
	s_cmp_ge_u32 s31, s19
	s_cbranch_scc1 .Lmf_lastVB
	s_add_i32 m0, s44, 25472
	s_nop 0
	global_load_lds_dwordx4 v[176:177], off offset:128
	global_load_lds_dwordx4 v[178:179], off offset:1152
	v_lshl_add_u64 v[176:177], v[176:177], 0, s[84:85]
	v_lshl_add_u64 v[178:179], v[178:179], 0, s[84:85]
	s_branch .Lmf_skipVB

; #define MFMA(a, b, c) __builtin_amdgcn_mfma_f32_32x32x16_bf16((a), (b), (c), 0, 0, 0)
; DI unsigned pack2(float a, float b) { f32x2v f = {a, b}; bf16x2v v = __builtin_convertvector(f, bf16x2v); return __builtin_bit_cast(unsigned, v); }
; DI float xhalf(float v) { return __shfl_xor(v, 32); }
;   template <int PAR>
;   DI void step(int t, f32x16 (&cur)[2], f32x16 (&nxt)[2]) {
;     if (t + 1 < nt) sstore_k(PAR ^ 1);
;     if (t > 0) sstore_v(PAR);
;     __syncthreads();
;     if (t + 1 < nt) qk(PAR ^ 1, nxt);
;     float mx = fmaxf(cur[0][0], cur[1][0]);
; #pragma unroll
;     for (int i = 1; i < 16; ++i) mx = fmaxf(fmaxf(cur[0][i], cur[1][i]), mx);
;     if (__builtin_amdgcn_ballot_w64(mx > ATT_THR) != 0ull) {
;       asm volatile("" ::: "memory");
;       mx = fmaxf(mx, xhalf(mx));
;       const float want = mref + fmaxf(mx, 0.f);
;       const float mn = __uint_as_float(pack2(want, 0.f) << 16);
;       const float d = mn - mref;
;       const float alpha = __builtin_amdgcn_exp2f(-d);
;       mref = mn;
;       l *= alpha;
; #pragma unroll
;       for (int a = 0; a < 2; ++a)
; #pragma unroll
;         for (int i = 0; i < 16; ++i) { o[a][i] *= alpha; cur[a][i] -= d; nxt[a][i] -= d; }
;       u32x4 q4 = {h == 0 ? (pack2(-mn, 0.f) & 0xffffu) : 0u, 0u, 0u, 0u};
;       qm = __builtin_bit_cast(bf16x8, q4);
;     }
;     float psum = 0.f;
; #pragma unroll
;     for (int kb2 = 0; kb2 < 2; ++kb2)
; #pragma unroll
;       for (int i = 0; i < 16; ++i) { const float pv = __builtin_amdgcn_exp2f(cur[kb2][i]); cur[kb2][i] = pv; psum += pv; }
;     l += psum;
;     if (t + 2 < nt) gload_k(t + 2);
;     if (t + 1 < nt) gload_v(t + 1);
;     const u16* vb = sV + PAR * VBUF + r * GP + h * 8;
; #pragma unroll
;     for (int kb2 = 0; kb2 < 2; ++kb2)
; #pragma unroll
;       for (int s2 = 0; s2 < 2; ++s2) {
;         u32x4 pk = {pack2(cur[kb2][8 * s2], cur[kb2][8 * s2 + 1]), pack2(cur[kb2][8 * s2 + 2], cur[kb2][8 * s2 + 3]),
;                     pack2(cur[kb2][8 * s2 + 4], cur[kb2][8 * s2 + 5]), pack2(cur[kb2][8 * s2 + 6], cur[kb2][8 * s2 + 7])};
;         const bf16x8 pf = __builtin_bit_cast(bf16x8, pk);
; #pragma unroll
;         for (int db = 0; db < 2; ++db) {
;           const bf16x8 a = *(const bf16x8*)(vb + db * 32 * GP + kb2 * 32 + s2 * 16);
;           o[db] = MFMA(a, pf, o[db]);
;         }
;       }
;   }
.Lmf_skipVB:
	v_mfma_f32_32x32x16_bf16 v[32:47], v[124:127], v[148:151], v[32:47]
	ds_read_b128 v[124:127], v167 offset:40960
	v_add_f32_e32 v238, v64, v238
	v_exp_f32_e32 v67, v67
	v_add_f32_e32 v239, v65, v239
	v_exp_f32_e32 v68, v68
	v_add_f32_e32 v238, v66, v238
	v_mfma_f32_32x32x16_bf16 v[48:63], v[96:99], v[152:155], v[48:63]
	ds_read_b128 v[96:99], v168 offset:36864
	v_exp_f32_e32 v69, v69
	v_add_f32_e32 v239, v67, v239
	v_exp_f32_e32 v70, v70
	v_add_f32_e32 v238, v68, v238
	v_mfma_f32_32x32x16_bf16 v[32:47], v[100:103], v[152:155], v[32:47]
	ds_read_b128 v[100:103], v168 offset:40960
	v_exp_f32_e32 v71, v71
	v_add_f32_e32 v239, v69, v239
	v_cvt_pk_bf16_f32 v64, v64, v65
	v_add_f32_e32 v238, v70, v238
	v_mfma_f32_32x32x16_bf16 v[48:63], v[104:107], v[156:159], v[48:63]
	ds_read_b128 v[104:107], v169 offset:36864
	v_cvt_pk_bf16_f32 v65, v66, v67
	v_add_f32_e32 v239, v71, v239
	v_cvt_pk_bf16_f32 v66, v68, v69
	v_cvt_pk_bf16_f32 v67, v70, v71
	v_mfma_f32_32x32x16_bf16 v[32:47], v[108:111], v[156:159], v[32:47]
	ds_read_b128 v[108:111], v169 offset:40960
	v_exp_f32_e32 v72, v72
	v_exp_f32_e32 v73, v73
	v_exp_f32_e32 v74, v74
	v_add_f32_e32 v238, v72, v238
	s_waitcnt lgkmcnt(4)
	v_mfma_f32_32x32x16_bf16 v[16:31], v[112:115], v[80:83], v[16:31]
	ds_read_b128 v[112:115], v162 offset:13312
	v_exp_f32_e32 v75, v75
	v_add_f32_e32 v239, v73, v239
	v_exp_f32_e32 v76, v76
	v_add_f32_e32 v238, v74, v238
	v_mfma_f32_32x32x16_bf16 v[0:15], v[116:119], v[80:83], v[0:15]
	ds_read_b128 v[116:119], v162 offset:17408
	v_exp_f32_e32 v77, v77
	v_add_f32_e32 v239, v75, v239
	v_exp_f32_e32 v78, v78
	v_add_f32_e32 v238, v76, v238
	v_mfma_f32_32x32x16_bf16 v[16:31], v[120:123], v[88:91], v[16:31]
	ds_read_b128 v[120:123], v163 offset:13312
	v_exp_f32_e32 v79, v79
	v_add_f32_e32 v239, v77, v239
	v_cvt_pk_bf16_f32 v72, v72, v73
	v_add_f32_e32 v238, v78, v238
	v_mfma_f32_32x32x16_bf16 v[0:15], v[124:127], v[88:91], v[0:15]
	ds_read_b128 v[124:127], v163 offset:17408
	v_cvt_pk_bf16_f32 v73, v74, v75
	v_add_f32_e32 v239, v79, v239
	v_cvt_pk_bf16_f32 v74, v76, v77
	v_cvt_pk_bf16_f32 v75, v78, v79
	s_waitcnt lgkmcnt(4)
	v_mfma_f32_32x32x16_bf16 v[16:31], v[96:99], v[64:67], v[16:31]
	ds_read_b128 v[96:99], v160 offset:13312
	v_max3_f32 v240, v48, v32, v49
	v_max3_f32 v241, v33, v50, v34
	v_max3_f32 v240, v51, v35, v240
	v_max3_f32 v241, v52, v36, v241
	v_mfma_f32_32x32x16_bf16 v[0:15], v[100:103], v[64:67], v[0:15]
	ds_read_b128 v[100:103], v160 offset:17408
	v_max3_f32 v240, v53, v37, v240
	v_max3_f32 v241, v54, v38, v241
	v_max3_f32 v240, v55, v39, v240
	v_max3_f32 v241, v56, v40, v241
	v_mfma_f32_32x32x16_bf16 v[16:31], v[104:107], v[72:75], v[16:31]
	ds_read_b128 v[104:107], v161 offset:13312
	v_max3_f32 v240, v57, v41, v240
	v_max3_f32 v241, v58, v42, v241
	v_max3_f32 v240, v59, v43, v240
	v_max3_f32 v241, v60, v44, v241
	v_mfma_f32_32x32x16_bf16 v[0:15], v[108:111], v[72:75], v[0:15]
	ds_read_b128 v[108:111], v161 offset:17408
	v_max3_f32 v240, v61, v45, v240
	v_max3_f32 v241, v62, v46, v241
	v_max3_f32 v240, v63, v47, v240
	v_max_f32_e32 v240, v240, v241
	v_lshl_add_u64 v[130:131], v[130:131], 0, s[84:85]
	v_lshl_add_u64 v[220:221], v[220:221], 0, s[84:85]
	s_mov_b32 s0, s31
	s_add_i32 s31, s31, 2
	s_cmp_lt_u32 s0, s19
	s_cbranch_scc1 .Lmf_top
	s_branch .Lm_fold

;   DI void gload_k(int t) {
;     const int row0 = rowk0 + t * 64;
;     const u16* kt = Kb + (size_t)row0 * kpitch;
;     const u16* pt = KPEb + (size_t)row0 * 32;
; #pragma unroll
;     for (int q = 0; q < NKL; ++q) {
;       const int c = tid + 256 * q, cc = c % KCH;
;       rk[q] = ldg16(((DQK == 96 && cc >= 8) ? pt : kt) + koff[q]);
;     }
;   template <int PAR>
;   DI void step(int t, f32x16 (&cur)[2], f32x16 (&nxt)[2]) {
;     if (t + 1 < nt) sstore_k(PAR ^ 1);
;     if (t > 0) sstore_v(PAR);
;     __syncthreads();
;     if (t + 1 < nt) qk(PAR ^ 1, nxt);
;     float mx = fmaxf(cur[0][0], cur[1][0]);
; #pragma unroll
;     for (int i = 1; i < 16; ++i) mx = fmaxf(fmaxf(cur[0][i], cur[1][i]), mx);
;     if (__builtin_amdgcn_ballot_w64(mx > ATT_THR) != 0ull) {
;       asm volatile("" ::: "memory");
;       mx = fmaxf(mx, xhalf(mx));
;       const float want = mref + fmaxf(mx, 0.f);
;       const float mn = __uint_as_float(pack2(want, 0.f) << 16);
;       const float d = mn - mref;
;       const float alpha = __builtin_amdgcn_exp2f(-d);
;       mref = mn;
;       l *= alpha;
; #pragma unroll
;       for (int a = 0; a < 2; ++a)
; #pragma unroll
;         for (int i = 0; i < 16; ++i) { o[a][i] *= alpha; cur[a][i] -= d; nxt[a][i] -= d; }
;       u32x4 q4 = {h == 0 ? (pack2(-mn, 0.f) & 0xffffu) : 0u, 0u, 0u, 0u};
;       qm = __builtin_bit_cast(bf16x8, q4);
;     }
;     float psum = 0.f;
; #pragma unroll
;     for (int kb2 = 0; kb2 < 2; ++kb2)
; #pragma unroll
;       for (int i = 0; i < 16; ++i) { const float pv = __builtin_amdgcn_exp2f(cur[kb2][i]); cur[kb2][i] = pv; psum += pv; }
;     l += psum;
;     if (t + 2 < nt) gload_k(t + 2);
;     if (t + 1 < nt) gload_v(t + 1);
;     const u16* vb = sV + PAR * VBUF + r * GP + h * 8;
; #pragma unroll
;     for (int kb2 = 0; kb2 < 2; ++kb2)
; #pragma unroll
;       for (int s2 = 0; s2 < 2; ++s2) {
;         u32x4 pk = {pack2(cur[kb2][8 * s2], cur[kb2][8 * s2 + 1]), pack2(cur[kb2][8 * s2 + 2], cur[kb2][8 * s2 + 3]),
;                     pack2(cur[kb2][8 * s2 + 4], cur[kb2][8 * s2 + 5]), pack2(cur[kb2][8 * s2 + 6], cur[kb2][8 * s2 + 7])};
;         const bf16x8 pf = __builtin_bit_cast(bf16x8, pk);
; #pragma unroll
;         for (int db = 0; db < 2; ++db) {
;           const bf16x8 a = *(const bf16x8*)(vb + db * 32 * GP + kb2 * 32 + s2 * 16);
;           o[db] = MFMA(a, pf, o[db]);
;         }
;       }
;   }
.Lm_skipKA:
	v_mfma_f32_32x32x16_bf16 v[80:95], v[112:115], v[144:147], v[80:95]
	ds_read_b128 v[112:115], v166 offset:25600
	v_exp_f32_e32 v59, v59
	v_add_f32_e32 v239, v57, v239
	v_exp_f32_e32 v60, v60
	v_add_f32_e32 v238, v58, v238
	v_mfma_f32_32x32x16_bf16 v[64:79], v[116:119], v[144:147], v[64:79]
	ds_read_b128 v[116:119], v166 offset:29696
	v_exp_f32_e32 v61, v61
	v_add_f32_e32 v239, v59, v239
	v_exp_f32_e32 v62, v62
	v_add_f32_e32 v238, v60, v238
	v_mfma_f32_32x32x16_bf16 v[80:95], v[120:123], v[148:151], v[80:95]
	ds_read_b128 v[120:123], v167 offset:25600
	v_exp_f32_e32 v63, v63
	v_add_f32_e32 v239, v61, v239
	v_cvt_pk_bf16_f32 v56, v56, v57
	v_add_f32_e32 v238, v62, v238
	s_add_i32 m0, s44, 36864
	s_nop 0
	global_load_lds_dwordx4 v[176:177], off
	global_load_lds_dwordx4 v[178:179], off offset:1024
	v_mfma_f32_32x32x16_bf16 v[64:79], v[124:127], v[148:151], v[64:79]
	ds_read_b128 v[124:127], v167 offset:29696
	v_cvt_pk_bf16_f32 v57, v58, v59
	v_add_f32_e32 v239, v63, v239
	v_cvt_pk_bf16_f32 v58, v60, v61
	v_cvt_pk_bf16_f32 v59, v62, v63
	v_mfma_f32_32x32x16_bf16 v[80:95], v[96:99], v[152:155], v[80:95]
	ds_read_b128 v[96:99], v168 offset:25600
	v_exp_f32_e32 v32, v32
	v_exp_f32_e32 v33, v33
	v_exp_f32_e32 v34, v34
	v_add_f32_e32 v238, v32, v238
	v_mfma_f32_32x32x16_bf16 v[64:79], v[100:103], v[152:155], v[64:79]
	ds_read_b128 v[100:103], v168 offset:29696
	v_exp_f32_e32 v35, v35
	v_add_f32_e32 v239, v33, v239
	v_exp_f32_e32 v36, v36
	v_add_f32_e32 v238, v34, v238
	v_mfma_f32_32x32x16_bf16 v[80:95], v[104:107], v[156:159], v[80:95]
	ds_read_b128 v[104:107], v169 offset:25600
	v_exp_f32_e32 v37, v37
	v_add_f32_e32 v239, v35, v239
	v_exp_f32_e32 v38, v38
	v_add_f32_e32 v238, v36, v238
	v_mfma_f32_32x32x16_bf16 v[64:79], v[108:111], v[156:159], v[64:79]
	ds_read_b128 v[108:111], v169 offset:29696
	v_exp_f32_e32 v39, v39
	v_add_f32_e32 v239, v37, v239
	v_cvt_pk_bf16_f32 v32, v32, v33
	v_add_f32_e32 v238, v38, v238
	v_mfma_f32_32x32x16_bf16 v[80:95], v[132:135], v[180:183], v[80:95]
	v_cvt_pk_bf16_f32 v33, v34, v35
	v_add_f32_e32 v239, v39, v239
	v_cvt_pk_bf16_f32 v34, v36, v37
	v_cvt_pk_bf16_f32 v35, v38, v39
	v_mfma_f32_32x32x16_bf16 v[64:79], v[132:135], v[180:183], v[64:79]
	v_exp_f32_e32 v40, v40
	v_exp_f32_e32 v41, v41
	v_exp_f32_e32 v42, v42
	v_add_f32_e32 v238, v40, v238
	s_waitcnt lgkmcnt(4)
	v_mfma_f32_32x32x16_bf16 v[16:31], v[112:115], v[48:51], v[16:31]
	ds_read_b128 v[112:115], v162
	v_exp_f32_e32 v43, v43
	v_add_f32_e32 v239, v41, v239
	v_exp_f32_e32 v44, v44
	v_add_f32_e32 v238, v42, v238
	v_mfma_f32_32x32x16_bf16 v[0:15], v[116:119], v[48:51], v[0:15]
	ds_read_b128 v[116:119], v162 offset:4096
	v_exp_f32_e32 v45, v45
	v_add_f32_e32 v239, v43, v239
	v_exp_f32_e32 v46, v46
	v_add_f32_e32 v238, v44, v238
	v_mfma_f32_32x32x16_bf16 v[16:31], v[120:123], v[56:59], v[16:31]
	ds_read_b128 v[120:123], v163
	v_exp_f32_e32 v47, v47
	v_add_f32_e32 v239, v45, v239
	v_cvt_pk_bf16_f32 v40, v40, v41
	v_add_f32_e32 v238, v46, v238
	v_mfma_f32_32x32x16_bf16 v[0:15], v[124:127], v[56:59], v[0:15]
	ds_read_b128 v[124:127], v163 offset:4096
	v_cvt_pk_bf16_f32 v41, v42, v43
	v_add_f32_e32 v239, v47, v239
	v_cvt_pk_bf16_f32 v42, v44, v45
	v_cvt_pk_bf16_f32 v43, v46, v47
	s_waitcnt lgkmcnt(4)
	v_mfma_f32_32x32x16_bf16 v[16:31], v[96:99], v[32:35], v[16:31]
	ds_read_b128 v[96:99], v160
	v_max3_f32 v240, v80, v64, v81
	v_max3_f32 v241, v65, v82, v66
	v_max3_f32 v240, v83, v67, v240
	v_max3_f32 v241, v84, v68, v241
	v_mfma_f32_32x32x16_bf16 v[0:15], v[100:103], v[32:35], v[0:15]
	ds_read_b128 v[100:103], v160 offset:4096
	v_max3_f32 v240, v85, v69, v240
	v_max3_f32 v241, v86, v70, v241
	v_max3_f32 v240, v87, v71, v240
	v_max3_f32 v241, v88, v72, v241
	v_mfma_f32_32x32x16_bf16 v[16:31], v[104:107], v[40:43], v[16:31]
	ds_read_b128 v[104:107], v161
	v_max3_f32 v240, v89, v73, v240
	v_max3_f32 v241, v90, v74, v241
	v_max3_f32 v240, v91, v75, v240
	v_max3_f32 v241, v92, v76, v241
	v_mfma_f32_32x32x16_bf16 v[0:15], v[108:111], v[40:43], v[0:15]
	ds_read_b128 v[108:111], v161 offset:4096
	v_max3_f32 v240, v93, v77, v240
	v_max3_f32 v241, v94, v78, v241
	v_max3_f32 v240, v95, v79, v240
	v_max_f32_e32 v240, v240, v241
	v_cmp_lt_f32_e32 vcc, s65, v240
	s_cbranch_vccnz .Lm_rareB

; #define MFMA(a, b, c) __builtin_amdgcn_mfma_f32_32x32x16_bf16((a), (b), (c), 0, 0, 0)
; DI float xhalf(float v) { return __shfl_xor(v, 32); }
;   DI void gload_v(int t) {
;     const u16* vt = Vt + (rowk0 + t * 64);
; #pragma unroll
;     for (int q = 0; q < 2; ++q) rv[q] = ldg16(vt + voff[q]);
;   }
;   template <int PAR>
;   DI void step(int t, f32x16 (&cur)[2], f32x16 (&nxt)[2]) {
;     if (t + 1 < nt) sstore_k(PAR ^ 1);
;     if (t > 0) sstore_v(PAR);
;     __syncthreads();
;     if (t + 1 < nt) qk(PAR ^ 1, nxt);
;     float mx = fmaxf(cur[0][0], cur[1][0]);
; #pragma unroll
;     for (int i = 1; i < 16; ++i) mx = fmaxf(fmaxf(cur[0][i], cur[1][i]), mx);
;     if (__builtin_amdgcn_ballot_w64(mx > ATT_THR) != 0ull) {
;       asm volatile("" ::: "memory");
;       mx = fmaxf(mx, xhalf(mx));
;       const float want = mref + fmaxf(mx, 0.f);
;       const float mn = __uint_as_float(pack2(want, 0.f) << 16);
;       const float d = mn - mref;
;       const float alpha = __builtin_amdgcn_exp2f(-d);
;       mref = mn;
;       l *= alpha;
; #pragma unroll
;       for (int a = 0; a < 2; ++a)
; #pragma unroll
;         for (int i = 0; i < 16; ++i) { o[a][i] *= alpha; cur[a][i] -= d; nxt[a][i] -= d; }
;       u32x4 q4 = {h == 0 ? (pack2(-mn, 0.f) & 0xffffu) : 0u, 0u, 0u, 0u};
;       qm = __builtin_bit_cast(bf16x8, q4);
;     }
;     float psum = 0.f;
; #pragma unroll
;     for (int kb2 = 0; kb2 < 2; ++kb2)
; #pragma unroll
;       for (int i = 0; i < 16; ++i) { const float pv = __builtin_amdgcn_exp2f(cur[kb2][i]); cur[kb2][i] = pv; psum += pv; }
;     l += psum;
;     if (t + 2 < nt) gload_k(t + 2);
;     if (t + 1 < nt) gload_v(t + 1);
;     const u16* vb = sV + PAR * VBUF + r * GP + h * 8;
; #pragma unroll
;     for (int kb2 = 0; kb2 < 2; ++kb2)
; #pragma unroll
;       for (int s2 = 0; s2 < 2; ++s2) {
;         u32x4 pk = {pack2(cur[kb2][8 * s2], cur[kb2][8 * s2 + 1]), pack2(cur[kb2][8 * s2 + 2], cur[kb2][8 * s2 + 3]),
;                     pack2(cur[kb2][8 * s2 + 4], cur[kb2][8 * s2 + 5]), pack2(cur[kb2][8 * s2 + 6], cur[kb2][8 * s2 + 7])};
;         const bf16x8 pf = __builtin_bit_cast(bf16x8, pk);
; #pragma unroll
;         for (int db = 0; db < 2; ++db) {
;           const bf16x8 a = *(const bf16x8*)(vb + db * 32 * GP + kb2 * 32 + s2 * 16);
;           o[db] = MFMA(a, pf, o[db]);
;         }
;       }
;   }
.Lm_skipKB:
	v_mfma_f32_32x32x16_bf16 v[48:63], v[112:115], v[144:147], v[48:63]
	ds_read_b128 v[112:115], v166 offset:36864
	v_exp_f32_e32 v91, v91
	v_add_f32_e32 v239, v89, v239
	v_exp_f32_e32 v92, v92
	v_add_f32_e32 v238, v90, v238
	v_mfma_f32_32x32x16_bf16 v[32:47], v[116:119], v[144:147], v[32:47]
	ds_read_b128 v[116:119], v166 offset:40960
	v_exp_f32_e32 v93, v93
	v_add_f32_e32 v239, v91, v239
	v_exp_f32_e32 v94, v94
	v_add_f32_e32 v238, v92, v238
	v_mfma_f32_32x32x16_bf16 v[48:63], v[120:123], v[148:151], v[48:63]
	ds_read_b128 v[120:123], v167 offset:36864
	v_exp_f32_e32 v95, v95
	v_add_f32_e32 v239, v93, v239
	v_cvt_pk_bf16_f32 v88, v88, v89
	v_add_f32_e32 v238, v94, v238
	s_cmp_ge_u32 s31, s19
	s_cbranch_scc1 .Lm_lastVB
	s_add_i32 m0, s44, 25472
	s_nop 0
	global_load_lds_dwordx4 v[176:177], off offset:128
	global_load_lds_dwordx4 v[178:179], off offset:1152
	v_lshl_add_u64 v[176:177], v[176:177], 0, s[84:85]
	v_lshl_add_u64 v[178:179], v[178:179], 0, s[84:85]
	s_branch .Lm_skipVB

; #define MFMA(a, b, c) __builtin_amdgcn_mfma_f32_32x32x16_bf16((a), (b), (c), 0, 0, 0)
; DI unsigned pack2(float a, float b) { f32x2v f = {a, b}; bf16x2v v = __builtin_convertvector(f, bf16x2v); return __builtin_bit_cast(unsigned, v); }
; DI float xhalf(float v) { return __shfl_xor(v, 32); }
;   template <int PAR>
;   DI void step(int t, f32x16 (&cur)[2], f32x16 (&nxt)[2]) {
;     if (t + 1 < nt) sstore_k(PAR ^ 1);
;     if (t > 0) sstore_v(PAR);
;     __syncthreads();
;     if (t + 1 < nt) qk(PAR ^ 1, nxt);
;     float mx = fmaxf(cur[0][0], cur[1][0]);
; #pragma unroll
;     for (int i = 1; i < 16; ++i) mx = fmaxf(fmaxf(cur[0][i], cur[1][i]), mx);
;     if (__builtin_amdgcn_ballot_w64(mx > ATT_THR) != 0ull) {
;       asm volatile("" ::: "memory");
;       mx = fmaxf(mx, xhalf(mx));
;       const float want = mref + fmaxf(mx, 0.f);
;       const float mn = __uint_as_float(pack2(want, 0.f) << 16);
;       const float d = mn - mref;
;       const float alpha = __builtin_amdgcn_exp2f(-d);
;       mref = mn;
;       l *= alpha;
; #pragma unroll
;       for (int a = 0; a < 2; ++a)
; #pragma unroll
;         for (int i = 0; i < 16; ++i) { o[a][i] *= alpha; cur[a][i] -= d; nxt[a][i] -= d; }
;       u32x4 q4 = {h == 0 ? (pack2(-mn, 0.f) & 0xffffu) : 0u, 0u, 0u, 0u};
;       qm = __builtin_bit_cast(bf16x8, q4);
;     }
;     float psum = 0.f;
; #pragma unroll
;     for (int kb2 = 0; kb2 < 2; ++kb2)
; #pragma unroll
;       for (int i = 0; i < 16; ++i) { const float pv = __builtin_amdgcn_exp2f(cur[kb2][i]); cur[kb2][i] = pv; psum += pv; }
;     l += psum;
;     if (t + 2 < nt) gload_k(t + 2);
;     if (t + 1 < nt) gload_v(t + 1);
;     const u16* vb = sV + PAR * VBUF + r * GP + h * 8;
; #pragma unroll
;     for (int kb2 = 0; kb2 < 2; ++kb2)
; #pragma unroll
;       for (int s2 = 0; s2 < 2; ++s2) {
;         u32x4 pk = {pack2(cur[kb2][8 * s2], cur[kb2][8 * s2 + 1]), pack2(cur[kb2][8 * s2 + 2], cur[kb2][8 * s2 + 3]),
;                     pack2(cur[kb2][8 * s2 + 4], cur[kb2][8 * s2 + 5]), pack2(cur[kb2][8 * s2 + 6], cur[kb2][8 * s2 + 7])};
;         const bf16x8 pf = __builtin_bit_cast(bf16x8, pk);
; #pragma unroll
;         for (int db = 0; db < 2; ++db) {
;           const bf16x8 a = *(const bf16x8*)(vb + db * 32 * GP + kb2 * 32 + s2 * 16);
;           o[db] = MFMA(a, pf, o[db]);
;         }
;       }
;   }
.Lm_skipVB:
	v_mfma_f32_32x32x16_bf16 v[32:47], v[124:127], v[148:151], v[32:47]
	ds_read_b128 v[124:127], v167 offset:40960
	v_cvt_pk_bf16_f32 v89, v90, v91
	v_add_f32_e32 v239, v95, v239
	v_cvt_pk_bf16_f32 v90, v92, v93
	v_cvt_pk_bf16_f32 v91, v94, v95
	v_mfma_f32_32x32x16_bf16 v[48:63], v[96:99], v[152:155], v[48:63]
	ds_read_b128 v[96:99], v168 offset:36864
	v_exp_f32_e32 v64, v64
	v_exp_f32_e32 v65, v65
	v_exp_f32_e32 v66, v66
	v_add_f32_e32 v238, v64, v238
	v_mfma_f32_32x32x16_bf16 v[32:47], v[100:103], v[152:155], v[32:47]
	ds_read_b128 v[100:103], v168 offset:40960
	v_exp_f32_e32 v67, v67
	v_add_f32_e32 v239, v65, v239
	v_exp_f32_e32 v68, v68
	v_add_f32_e32 v238, v66, v238
	v_mfma_f32_32x32x16_bf16 v[48:63], v[104:107], v[156:159], v[48:63]
	ds_read_b128 v[104:107], v169 offset:36864
	v_exp_f32_e32 v69, v69
	v_add_f32_e32 v239, v67, v239
	v_exp_f32_e32 v70, v70
	v_add_f32_e32 v238, v68, v238
	v_mfma_f32_32x32x16_bf16 v[32:47], v[108:111], v[156:159], v[32:47]
	ds_read_b128 v[108:111], v169 offset:40960
	v_exp_f32_e32 v71, v71
	v_add_f32_e32 v239, v69, v239
	v_cvt_pk_bf16_f32 v64, v64, v65
	v_add_f32_e32 v238, v70, v238
	v_mfma_f32_32x32x16_bf16 v[48:63], v[132:135], v[180:183], v[48:63]
	v_cvt_pk_bf16_f32 v65, v66, v67
	v_add_f32_e32 v239, v71, v239
	v_cvt_pk_bf16_f32 v66, v68, v69
	v_cvt_pk_bf16_f32 v67, v70, v71
	v_mfma_f32_32x32x16_bf16 v[32:47], v[132:135], v[180:183], v[32:47]
	v_exp_f32_e32 v72, v72
	v_exp_f32_e32 v73, v73
	v_exp_f32_e32 v74, v74
	v_add_f32_e32 v238, v72, v238
	s_waitcnt lgkmcnt(4)
	v_mfma_f32_32x32x16_bf16 v[16:31], v[112:115], v[80:83], v[16:31]
	ds_read_b128 v[112:115], v162 offset:13312
	v_exp_f32_e32 v75, v75
	v_add_f32_e32 v239, v73, v239
	v_exp_f32_e32 v76, v76
	v_add_f32_e32 v238, v74, v238
	v_mfma_f32_32x32x16_bf16 v[0:15], v[116:119], v[80:83], v[0:15]
	ds_read_b128 v[116:119], v162 offset:17408
	v_exp_f32_e32 v77, v77
	v_add_f32_e32 v239, v75, v239
	v_exp_f32_e32 v78, v78
	v_add_f32_e32 v238, v76, v238
	v_mfma_f32_32x32x16_bf16 v[16:31], v[120:123], v[88:91], v[16:31]
	ds_read_b128 v[120:123], v163 offset:13312
	v_exp_f32_e32 v79, v79
	v_add_f32_e32 v239, v77, v239
	v_cvt_pk_bf16_f32 v72, v72, v73
	v_add_f32_e32 v238, v78, v238
	v_mfma_f32_32x32x16_bf16 v[0:15], v[124:127], v[88:91], v[0:15]
	ds_read_b128 v[124:127], v163 offset:17408
	v_cvt_pk_bf16_f32 v73, v74, v75
	v_add_f32_e32 v239, v79, v239
	v_cvt_pk_bf16_f32 v74, v76, v77
	v_cvt_pk_bf16_f32 v75, v78, v79
	s_waitcnt lgkmcnt(4)
	v_mfma_f32_32x32x16_bf16 v[16:31], v[96:99], v[64:67], v[16:31]
	ds_read_b128 v[96:99], v160 offset:13312
	v_max3_f32 v240, v48, v32, v49
	v_max3_f32 v241, v33, v50, v34
	v_max3_f32 v240, v51, v35, v240
	v_max3_f32 v241, v52, v36, v241
	v_mfma_f32_32x32x16_bf16 v[0:15], v[100:103], v[64:67], v[0:15]
	ds_read_b128 v[100:103], v160 offset:17408
	v_max3_f32 v240, v53, v37, v240
	v_max3_f32 v241, v54, v38, v241
	v_max3_f32 v240, v55, v39, v240
	v_max3_f32 v241, v56, v40, v241
	v_mfma_f32_32x32x16_bf16 v[16:31], v[104:107], v[72:75], v[16:31]
	ds_read_b128 v[104:107], v161 offset:13312
	v_max3_f32 v240, v57, v41, v240
	v_max3_f32 v241, v58, v42, v241
	v_max3_f32 v240, v59, v43, v240
	v_max3_f32 v241, v60, v44, v241
	v_mfma_f32_32x32x16_bf16 v[0:15], v[108:111], v[72:75], v[0:15]
	ds_read_b128 v[108:111], v161 offset:17408
	v_max3_f32 v240, v61, v45, v240
	v_max3_f32 v241, v62, v46, v241
	v_max3_f32 v240, v63, v47, v240
	v_max_f32_e32 v240, v240, v241
	v_lshl_add_u64 v[130:131], v[130:131], 0, s[84:85]
	v_lshl_add_u64 v[220:221], v[220:221], 0, s[84:85]
	s_mov_b32 s0, s31
	s_add_i32 s31, s31, 2
	s_cmp_lt_u32 s0, s19
	s_cbranch_scc1 .LBB0_268
	s_branch .Lm_fold
